# v9 + causal-unit gate (G) loads hoisted to the final step's PV phase
# baseline (speedup 1.0000x reference)
.LBB0_546:
	s_or_b64 exec, exec, s[0:1]
	s_waitcnt lgkmcnt(0)
	ds_read_b128 v[32:35], v215 offset:128
	ds_read_b128 v[36:39], v215 offset:160
	s_lshl_b64 s[0:1], s[56:57], 24
	v_readlane_b32 s8, v246, 45
	s_add_u32 s8, s8, s0
	v_readlane_b32 s9, v246, 46
	s_waitcnt lgkmcnt(1)
	v_rcp_f32_e32 v40, v32
	s_addc_u32 s9, s9, s1
	s_add_u32 s44, s8, s58
	v_rcp_f32_e32 v41, v33
	s_addc_u32 s45, s9, s59
	v_readlane_b32 s8, v246, 47
	s_add_u32 s0, s8, s0
	v_mul_f32_e32 v0, v0, v40
	v_cvt_pk_bf16_f32 v0, v0, s0
	v_rcp_f32_e32 v42, v34
	ds_write_b16 v217, v0 offset:64
	v_mul_f32_e32 v0, v17, v41
	v_cvt_pk_bf16_f32 v0, v0, s0
	ds_write_b16 v217, v0 offset:128
	v_mul_f32_e32 v0, v1, v41
	v_cvt_pk_bf16_f32 v0, v0, s0
	v_rcp_f32_e32 v43, v35
	ds_write_b16 v217, v0 offset:192
	v_mul_f32_e32 v0, v18, v42
	v_cvt_pk_bf16_f32 v0, v0, s0
	ds_write_b16 v217, v0 offset:256
	v_mul_f32_e32 v0, v2, v42
	v_cvt_pk_bf16_f32 v0, v0, s0
	s_waitcnt lgkmcnt(4)
	v_rcp_f32_e32 v44, v36
	ds_write_b16 v217, v0 offset:320
	v_mul_f32_e32 v0, v19, v43
	v_cvt_pk_bf16_f32 v0, v0, s0
	ds_write_b16 v217, v0 offset:384
	v_mul_f32_e32 v0, v3, v43
	v_cvt_pk_bf16_f32 v0, v0, s0
	v_rcp_f32_e32 v45, v37
	ds_write_b16 v217, v0 offset:448
	v_mul_f32_e32 v0, v20, v44
	v_cvt_pk_bf16_f32 v0, v0, s0
	ds_write_b16 v217, v0 offset:1024
	v_mul_f32_e32 v0, v4, v44
	v_cvt_pk_bf16_f32 v0, v0, s0
	v_rcp_f32_e32 v46, v38
	ds_write_b16 v217, v0 offset:1088
	v_mul_f32_e32 v0, v21, v45
	v_cvt_pk_bf16_f32 v0, v0, s0
	ds_write_b16 v217, v0 offset:1152
	v_mul_f32_e32 v0, v5, v45
	ds_read_b128 v[32:35], v215 offset:192
	v_cvt_pk_bf16_f32 v0, v0, s0
	v_rcp_f32_e32 v47, v39
	ds_write_b16 v217, v0 offset:1216
	v_mul_f32_e32 v0, v22, v46
	v_cvt_pk_bf16_f32 v0, v0, s0
	ds_write_b16 v217, v0 offset:1280
	v_mul_f32_e32 v0, v6, v46
	v_cvt_pk_bf16_f32 v0, v0, s0
	ds_read_b128 v[36:39], v215 offset:224
	s_waitcnt lgkmcnt(3)
	v_rcp_f32_e32 v32, v32
	ds_write_b16 v217, v0 offset:1344
	v_mul_f32_e32 v0, v23, v47
	v_cvt_pk_bf16_f32 v0, v0, s0
	ds_write_b16 v217, v0 offset:1408
	v_mul_f32_e32 v0, v7, v47
	v_cvt_pk_bf16_f32 v0, v0, s0
	v_rcp_f32_e32 v33, v33
	ds_write_b16 v217, v0 offset:1472
	v_mul_f32_e32 v0, v24, v32
	v_cvt_pk_bf16_f32 v0, v0, s0
	ds_write_b16 v217, v0 offset:2048
	v_mul_f32_e32 v0, v8, v32
	v_cvt_pk_bf16_f32 v0, v0, s0
	v_rcp_f32_e32 v34, v34
	ds_write_b16 v217, v0 offset:2112
	v_mul_f32_e32 v0, v25, v33
	v_cvt_pk_bf16_f32 v0, v0, s0
	ds_write_b16 v217, v0 offset:2176
	v_mul_f32_e32 v0, v9, v33
	v_cvt_pk_bf16_f32 v0, v0, s0
	v_rcp_f32_e32 v35, v35
	ds_write_b16 v217, v0 offset:2240
	v_mul_f32_e32 v0, v26, v34
	v_cvt_pk_bf16_f32 v0, v0, s0
	ds_write_b16 v217, v0 offset:2304
	v_mul_f32_e32 v0, v10, v34
	v_cvt_pk_bf16_f32 v0, v0, s0
	s_waitcnt lgkmcnt(8)
	v_rcp_f32_e32 v36, v36
	ds_write_b16 v217, v0 offset:2368
	v_mul_f32_e32 v0, v27, v35
	v_cvt_pk_bf16_f32 v0, v0, s0
	ds_write_b16 v217, v0 offset:2432
	v_mul_f32_e32 v0, v11, v35
	v_cvt_pk_bf16_f32 v0, v0, s0
	v_rcp_f32_e32 v37, v37
	ds_write_b16 v217, v0 offset:2496
	v_mul_f32_e32 v0, v28, v36
	v_cvt_pk_bf16_f32 v0, v0, s0
	ds_write_b16 v217, v0 offset:3072
	v_mul_f32_e32 v0, v12, v36
	v_cvt_pk_bf16_f32 v0, v0, s0
	v_rcp_f32_e32 v38, v38
	ds_write_b16 v217, v0 offset:3136
	v_mul_f32_e32 v0, v29, v37
	v_cvt_pk_bf16_f32 v0, v0, s0
	ds_write_b16 v217, v0 offset:3200
	v_mul_f32_e32 v0, v13, v37
	v_cvt_pk_bf16_f32 v0, v0, s0
	v_rcp_f32_e32 v39, v39
	ds_write_b16 v217, v0 offset:3264
	v_mul_f32_e32 v0, v30, v38
	v_cvt_pk_bf16_f32 v0, v0, s0
	ds_write_b16 v217, v0 offset:3328
	v_mul_f32_e32 v0, v14, v38
	v_cvt_pk_bf16_f32 v0, v0, s0
	v_readlane_b32 s8, v246, 48
	ds_write_b16 v217, v0 offset:3392
	v_mul_f32_e32 v0, v31, v39
	s_addc_u32 s1, s8, s1
	v_cvt_pk_bf16_f32 v0, v0, s0
	s_add_u32 s8, s0, s58
	v_mul_f32_e32 v16, v16, v40
	ds_write_b16 v217, v0 offset:3456
	v_mul_f32_e32 v0, v15, v39
	s_addc_u32 s9, s1, s59
	v_cvt_pk_bf16_f32 v16, v16, s0
	v_cvt_pk_bf16_f32 v0, v0, s0
	s_lshl_b64 s[0:1], s[52:53], 11
	s_add_u32 s44, s44, s0
	s_addc_u32 s45, s45, s1
	v_mov_b32_e32 v145, v153
	ds_write_b16 v217, v16
	ds_write_b16 v217, v0 offset:3520
	v_lshlrev_b64 v[140:141], 1, v[154:155]
	s_waitcnt lgkmcnt(0)
	v_lshlrev_b64 v[142:143], 1, v[156:157]
	v_lshlrev_b64 v[166:167], 1, v[158:159]
	v_lshlrev_b64 v[168:169], 1, v[160:161]
	ds_read_b128 v[12:15], v177
	s_add_u32 s0, s8, s0
	s_addc_u32 s1, s9, s1
	v_lshl_add_u64 v[20:21], s[0:1], 0, v[144:145]
	s_add_i32 s78, s78, 1
	s_waitcnt lgkmcnt(0)
	v_lshlrev_b32_e32 v22, 16, v12
	v_and_b32_e32 v23, 0xffff0000, v12
	v_lshlrev_b32_e32 v12, 16, v13
	v_and_b32_e32 v13, 0xffff0000, v13
	s_cmp_eq_u32 s78, 3
	s_waitcnt vmcnt(3)
	v_lshlrev_b32_e32 v24, 16, v80
	v_and_b32_e32 v25, 0xffff0000, v80
	v_pk_mul_f32 v[22:23], v[22:23], v[24:25]
	v_lshlrev_b32_e32 v24, 16, v83
	v_cvt_pk_bf16_f32 v0, v22, v23
	v_lshlrev_b32_e32 v22, 16, v81
	v_and_b32_e32 v23, 0xffff0000, v81
	v_pk_mul_f32 v[12:13], v[12:13], v[22:23]
	v_lshlrev_b32_e32 v22, 16, v82
	v_cvt_pk_bf16_f32 v1, v12, v13
	v_lshlrev_b32_e32 v12, 16, v14
	v_and_b32_e32 v13, 0xffff0000, v14
	v_and_b32_e32 v23, 0xffff0000, v82
	v_pk_mul_f32 v[12:13], v[12:13], v[22:23]
	v_lshlrev_b32_e32 v22, 16, v15
	v_cvt_pk_bf16_f32 v2, v12, v13
	v_and_b32_e32 v23, 0xffff0000, v15
	ds_read_b128 v[12:15], v176
	v_and_b32_e32 v25, 0xffff0000, v83
	v_pk_mul_f32 v[22:23], v[22:23], v[24:25]
	s_nop 0
	v_cvt_pk_bf16_f32 v3, v22, v23
	v_lshl_add_u64 v[22:23], v[20:21], 0, v[140:141]
	global_store_dwordx4 v[22:23], v[0:3], off sc1
	s_waitcnt lgkmcnt(0)
	s_nop 0
	v_lshlrev_b32_e32 v0, 16, v12
	v_and_b32_e32 v1, 0xffff0000, v12
	s_waitcnt vmcnt(3)
	v_lshlrev_b32_e32 v2, 16, v84
	v_and_b32_e32 v3, 0xffff0000, v84
	v_pk_mul_f32 v[0:1], v[0:1], v[2:3]
	v_lshlrev_b32_e32 v2, 16, v13
	v_and_b32_e32 v3, 0xffff0000, v13
	v_lshlrev_b32_e32 v4, 16, v85
	v_and_b32_e32 v5, 0xffff0000, v85
	v_pk_mul_f32 v[2:3], v[2:3], v[4:5]
	v_cvt_pk_bf16_f32 v0, v0, v1
	v_cvt_pk_bf16_f32 v1, v2, v3
	v_lshlrev_b32_e32 v2, 16, v14
	v_and_b32_e32 v3, 0xffff0000, v14
	v_lshlrev_b32_e32 v4, 16, v86
	v_and_b32_e32 v5, 0xffff0000, v86
	v_pk_mul_f32 v[2:3], v[2:3], v[4:5]
	v_lshlrev_b32_e32 v12, 16, v15
	v_and_b32_e32 v13, 0xffff0000, v15
	v_lshlrev_b32_e32 v14, 16, v87
	v_and_b32_e32 v15, 0xffff0000, v87
	ds_read_b128 v[4:7], v175
	v_pk_mul_f32 v[12:13], v[12:13], v[14:15]
	v_cvt_pk_bf16_f32 v2, v2, v3
	v_cvt_pk_bf16_f32 v3, v12, v13
	v_lshl_add_u64 v[12:13], v[20:21], 0, v[142:143]
	global_store_dwordx4 v[12:13], v[0:3], off sc1
	s_waitcnt lgkmcnt(0)
	s_nop 0
	v_lshlrev_b32_e32 v0, 16, v4
	v_and_b32_e32 v1, 0xffff0000, v4
	s_waitcnt vmcnt(3)
	v_lshlrev_b32_e32 v2, 16, v88
	v_and_b32_e32 v3, 0xffff0000, v88
	v_pk_mul_f32 v[0:1], v[0:1], v[2:3]
	v_lshlrev_b32_e32 v2, 16, v5
	v_and_b32_e32 v3, 0xffff0000, v5
	v_lshlrev_b32_e32 v4, 16, v89
	v_and_b32_e32 v5, 0xffff0000, v89
	v_pk_mul_f32 v[2:3], v[2:3], v[4:5]
	v_cvt_pk_bf16_f32 v0, v0, v1
	v_cvt_pk_bf16_f32 v1, v2, v3
	v_lshlrev_b32_e32 v2, 16, v6
	v_and_b32_e32 v3, 0xffff0000, v6
	v_lshlrev_b32_e32 v4, 16, v90
	v_and_b32_e32 v5, 0xffff0000, v90
	v_pk_mul_f32 v[2:3], v[2:3], v[4:5]
	v_lshlrev_b32_e32 v8, 16, v7
	v_and_b32_e32 v9, 0xffff0000, v7
	ds_read_b128 v[4:7], v174
	v_lshlrev_b32_e32 v10, 16, v91
	v_and_b32_e32 v11, 0xffff0000, v91
	v_pk_mul_f32 v[8:9], v[8:9], v[10:11]
	v_cvt_pk_bf16_f32 v2, v2, v3
	v_cvt_pk_bf16_f32 v3, v8, v9
	v_lshl_add_u64 v[8:9], v[20:21], 0, v[166:167]
	global_store_dwordx4 v[8:9], v[0:3], off sc1
	s_waitcnt lgkmcnt(0)
	s_nop 0
	v_lshlrev_b32_e32 v0, 16, v4
	v_and_b32_e32 v1, 0xffff0000, v4
	s_waitcnt vmcnt(3)
	v_lshlrev_b32_e32 v2, 16, v92
	v_and_b32_e32 v3, 0xffff0000, v92
	v_pk_mul_f32 v[0:1], v[0:1], v[2:3]
	v_lshlrev_b32_e32 v2, 16, v5
	v_and_b32_e32 v3, 0xffff0000, v5
	v_lshlrev_b32_e32 v4, 16, v93
	v_and_b32_e32 v5, 0xffff0000, v93
	v_pk_mul_f32 v[2:3], v[2:3], v[4:5]
	v_cvt_pk_bf16_f32 v0, v0, v1
	v_cvt_pk_bf16_f32 v1, v2, v3
	v_lshlrev_b32_e32 v2, 16, v6
	v_and_b32_e32 v3, 0xffff0000, v6
	v_lshlrev_b32_e32 v4, 16, v94
	v_and_b32_e32 v5, 0xffff0000, v94
	v_pk_mul_f32 v[2:3], v[2:3], v[4:5]
	v_lshlrev_b32_e32 v4, 16, v7
	v_and_b32_e32 v5, 0xffff0000, v7
	v_lshlrev_b32_e32 v6, 16, v95
	v_and_b32_e32 v7, 0xffff0000, v95
	v_pk_mul_f32 v[4:5], v[4:5], v[6:7]
	v_cvt_pk_bf16_f32 v2, v2, v3
	v_cvt_pk_bf16_f32 v3, v4, v5
	v_lshl_add_u64 v[4:5], v[20:21], 0, v[168:169]
	global_store_dwordx4 v[4:5], v[0:3], off sc1
	s_waitcnt lgkmcnt(0)
	s_barrier
	s_cbranch_scc1 .LBB0_668

.LBB0_660:
	s_lshl_b64 s[98:99], s[56:57], 24
	v_readlane_b32 s100, v246, 45
	v_readlane_b32 s101, v246, 46
	s_add_u32 s98, s100, s98
	s_addc_u32 s99, s101, s99
	s_add_u32 s98, s98, s58
	s_addc_u32 s99, s99, s59
	s_lshl_b64 s[100:101], s[52:53], 11
	s_add_u32 s98, s98, s100
	s_addc_u32 s99, s99, s101
	v_mov_b32_e32 v94, v144
	v_mov_b32_e32 v95, v153
	v_lshlrev_b64 v[80:81], 1, v[154:155]
	v_lshlrev_b64 v[84:85], 1, v[156:157]
	v_lshlrev_b64 v[88:89], 1, v[158:159]
	v_lshlrev_b64 v[92:93], 1, v[160:161]
	v_lshl_add_u64 v[94:95], s[98:99], 0, v[94:95]
	v_lshl_add_u64 v[80:81], v[94:95], 0, v[80:81]
	v_lshl_add_u64 v[84:85], v[94:95], 0, v[84:85]
	v_lshl_add_u64 v[88:89], v[94:95], 0, v[88:89]
	v_lshl_add_u64 v[92:93], v[94:95], 0, v[92:93]
	global_load_dwordx4 v[80:83], v[80:81], off
	global_load_dwordx4 v[84:87], v[84:85], off
	global_load_dwordx4 v[88:91], v[88:89], off
	global_load_dwordx4 v[92:95], v[92:93], off
	ds_read_b64_tr_b16 v[64:65], v167 offset:54272
	ds_read_b64_tr_b16 v[66:67], v167 offset:54784
	s_waitcnt lgkmcnt(6)
	v_mfma_f32_32x32x16_bf16 v[16:31], v[132:135], v[96:99], v[16:31]
	v_exp_f32_e32 v48, v48
	v_exp_f32_e32 v49, v49
	v_exp_f32_e32 v50, v50
	v_exp_f32_e32 v51, v51
	ds_read_b64_tr_b16 v[68:69], v167 offset:51200
	ds_read_b64_tr_b16 v[70:71], v167 offset:51712
	s_waitcnt lgkmcnt(6)
	v_mfma_f32_32x32x16_bf16 v[0:15], v[132:135], v[108:111], v[0:15]
	v_exp_f32_e32 v52, v52
	v_exp_f32_e32 v53, v53
	v_exp_f32_e32 v54, v54
	v_exp_f32_e32 v55, v55
	ds_read_b64_tr_b16 v[72:73], v167 offset:55296
	ds_read_b64_tr_b16 v[74:75], v167 offset:55808
	s_waitcnt lgkmcnt(6)
	v_mfma_f32_32x32x16_bf16 v[16:31], v[128:131], v[104:107], v[16:31]
	v_exp_f32_e32 v56, v56
	v_exp_f32_e32 v57, v57
	v_exp_f32_e32 v58, v58
	v_exp_f32_e32 v59, v59
	ds_read_b64_tr_b16 v[76:77], v167 offset:52224
	ds_read_b64_tr_b16 v[78:79], v167 offset:52736
	s_waitcnt lgkmcnt(6)
	v_mfma_f32_32x32x16_bf16 v[0:15], v[128:131], v[64:67], v[0:15]
	v_exp_f32_e32 v60, v60
	v_exp_f32_e32 v61, v61
	v_exp_f32_e32 v62, v62
	v_exp_f32_e32 v63, v63
	ds_read_b64_tr_b16 v[64:65], v167 offset:56320
	ds_read_b64_tr_b16 v[66:67], v167 offset:56832
	s_waitcnt lgkmcnt(6)
	v_mfma_f32_32x32x16_bf16 v[16:31], v[124:127], v[68:71], v[16:31]
	v_exp_f32_e32 v32, v32
	v_exp_f32_e32 v33, v33
	v_exp_f32_e32 v34, v34
	v_exp_f32_e32 v35, v35
	s_waitcnt lgkmcnt(4)
	v_mfma_f32_32x32x16_bf16 v[0:15], v[124:127], v[72:75], v[0:15]
	v_exp_f32_e32 v36, v36
	v_exp_f32_e32 v37, v37
	v_exp_f32_e32 v38, v38
	v_exp_f32_e32 v39, v39
	s_waitcnt lgkmcnt(2)
	v_mfma_f32_32x32x16_bf16 v[16:31], v[120:123], v[76:79], v[16:31]
	v_exp_f32_e32 v40, v40
	v_exp_f32_e32 v41, v41
	v_exp_f32_e32 v42, v42
	v_exp_f32_e32 v43, v43
	s_waitcnt lgkmcnt(0)
	v_mfma_f32_32x32x16_bf16 v[0:15], v[120:123], v[64:67], v[0:15]
	v_exp_f32_e32 v44, v44
	v_exp_f32_e32 v45, v45
	v_exp_f32_e32 v46, v46
	v_exp_f32_e32 v47, v47
	s_andn2_b64 vcc, exec, s[60:61]
	s_cbranch_vccnz .LBB0_662
	s_waitcnt lgkmcnt(0)
	ds_read_b128 v[64:67], v215 offset:96
	ds_read_b128 v[68:71], v215 offset:64
	ds_read_b128 v[72:75], v215 offset:32
	ds_read_b128 v[76:79], v215
	s_waitcnt lgkmcnt(3)
	v_pk_mul_f32 v[30:31], v[30:31], v[66:67]
	s_waitcnt lgkmcnt(2)
	v_pk_mul_f32 v[26:27], v[26:27], v[70:71]
	s_waitcnt lgkmcnt(1)
	v_pk_mul_f32 v[22:23], v[22:23], v[74:75]
	s_waitcnt lgkmcnt(0)
	v_pk_mul_f32 v[18:19], v[18:19], v[78:79]
	v_pk_mul_f32 v[28:29], v[28:29], v[64:65]
	v_pk_mul_f32 v[24:25], v[24:25], v[68:69]
	v_pk_mul_f32 v[20:21], v[20:21], v[72:73]
	v_pk_mul_f32 v[16:17], v[16:17], v[76:77]
	v_pk_mul_f32 v[14:15], v[14:15], v[66:67]
	v_pk_mul_f32 v[10:11], v[10:11], v[70:71]
	v_pk_mul_f32 v[6:7], v[6:7], v[74:75]
	v_pk_mul_f32 v[2:3], v[2:3], v[78:79]
	v_pk_mul_f32 v[12:13], v[12:13], v[64:65]
	v_pk_mul_f32 v[8:9], v[8:9], v[68:69]
	v_pk_mul_f32 v[4:5], v[4:5], v[72:73]
	v_pk_mul_f32 v[0:1], v[0:1], v[76:77]

	.amdhsa_kernel _Z8mega_fwd4Args
		.amdhsa_group_segment_fixed_size 0
		.amdhsa_private_segment_fixed_size 0
		.amdhsa_kernarg_size 448
		.amdhsa_user_sgpr_count 2
		.amdhsa_user_sgpr_dispatch_ptr 0
		.amdhsa_user_sgpr_queue_ptr 0
		.amdhsa_user_sgpr_kernarg_segment_ptr 1
		.amdhsa_user_sgpr_dispatch_id 0
		.amdhsa_user_sgpr_kernarg_preload_length 0
		.amdhsa_user_sgpr_kernarg_preload_offset 0
		.amdhsa_user_sgpr_private_segment_size 0
		.amdhsa_uses_dynamic_stack 0
		.amdhsa_enable_private_segment 0
		.amdhsa_system_sgpr_workgroup_id_x 1
		.amdhsa_system_sgpr_workgroup_id_y 0
		.amdhsa_system_sgpr_workgroup_id_z 0
		.amdhsa_system_sgpr_workgroup_info 0
		.amdhsa_system_vgpr_workitem_id 0
		.amdhsa_next_free_vgpr 247
		.amdhsa_next_free_sgpr 102
		.amdhsa_accum_offset 248
		.amdhsa_reserve_vcc 1
		.amdhsa_float_round_mode_32 0
		.amdhsa_float_round_mode_16_64 0
		.amdhsa_float_denorm_mode_32 3
		.amdhsa_float_denorm_mode_16_64 3
		.amdhsa_dx10_clamp 1
		.amdhsa_ieee_mode 1
		.amdhsa_fp16_overflow 0
		.amdhsa_tg_split 0
		.amdhsa_exception_fp_ieee_invalid_op 0
		.amdhsa_exception_fp_denorm_src 0
		.amdhsa_exception_fp_ieee_div_zero 0
		.amdhsa_exception_fp_ieee_overflow 0
		.amdhsa_exception_fp_ieee_underflow 0
		.amdhsa_exception_fp_ieee_inexact 0
		.amdhsa_exception_int_div_zero 0
	.end_amdhsa_kernel

amdhsa.kernels:
  - .agpr_count:     0
    .args:
      - .offset:         0
        .size:           192
        .value_kind:     by_value
      - .offset:         192
        .size:           4
        .value_kind:     hidden_block_count_x
      - .offset:         196
        .size:           4
        .value_kind:     hidden_block_count_y
      - .offset:         200
        .size:           4
        .value_kind:     hidden_block_count_z
      - .offset:         204
        .size:           2
        .value_kind:     hidden_group_size_x
      - .offset:         206
        .size:           2
        .value_kind:     hidden_group_size_y
      - .offset:         208
        .size:           2
        .value_kind:     hidden_group_size_z
      - .offset:         210
        .size:           2
        .value_kind:     hidden_remainder_x
      - .offset:         212
        .size:           2
        .value_kind:     hidden_remainder_y
      - .offset:         214
        .size:           2
        .value_kind:     hidden_remainder_z
      - .offset:         232
        .size:           8
        .value_kind:     hidden_global_offset_x
      - .offset:         240
        .size:           8
        .value_kind:     hidden_global_offset_y
      - .offset:         248
        .size:           8
        .value_kind:     hidden_global_offset_z
      - .offset:         256
        .size:           2
        .value_kind:     hidden_grid_dims
      - .offset:         312
        .size:           4
        .value_kind:     hidden_dynamic_lds_size
    .group_segment_fixed_size: 0
    .kernarg_segment_align: 8
    .kernarg_segment_size: 448
    .language:       OpenCL C
    .language_version:
      - 2
      - 0
    .max_flat_workgroup_size: 512
    .name:           _Z8mega_fwd4Args
    .private_segment_fixed_size: 0
    .sgpr_count:     108
    .sgpr_spill_count: 151
    .symbol:         _Z8mega_fwd4Args.kd
    .uniform_work_group_size: 1
    .uses_dynamic_stack: false
    .vgpr_count:     247
    .vgpr_spill_count: 0
    .wavefront_size: 64
